# non-blocking cross-chunk prefetch: when helper wave 0 has published the next chunk's first sub-chunk (LDS flag), the compute waves fetch its operands and X-init under the last SA/Y MFMAs and skip the
# speedup vs baseline: 1.0011x; 1.0011x over previous
.Lmy_f_main:
	s_cmpk_ge_u32 s62, 0x100
	s_cbranch_scc1 .Lmy_f_hlp
	s_cmp_lg_u32 s65, 0
	s_cbranch_scc1 .Lmy_ck_nz
	v_mov_b32_e32 v208, 0
	v_mov_b32_e32 v209, 0
	v_mov_b32_e32 v210, 0
	v_mov_b32_e32 v211, 0
	v_mov_b32_e32 v212, 0
	v_mov_b32_e32 v213, 0
	v_mov_b32_e32 v214, 0
	v_mov_b32_e32 v215, 0
	v_mov_b32_e32 v216, 0
	v_mov_b32_e32 v217, 0
	v_mov_b32_e32 v218, 0
	v_mov_b32_e32 v219, 0
	v_mov_b32_e32 v220, 0
	v_mov_b32_e32 v221, 0
	v_mov_b32_e32 v222, 0
	v_mov_b32_e32 v223, 0
	v_mov_b32_e32 v18, 0x22040
	s_mov_b32 s25, 0
	v_xor_b32_e32 v1, v224, v234
	v_lshlrev_b32_e32 v1, 4, v1
	v_lshlrev_b32_e32 v2, 4, v234
	v_add_u32_e32 v2, 0x2000, v2
	v_mov_b32_e32 v72, 0x2600
	v_mov_b32_e32 v73, 0x2500
	v_mov_b32_e32 v74, 0x2510
	v_mov_b32_e32 v75, 0x2590
	v_cmp_eq_u32_e64 s[96:97], 0, v234
	v_and_b32_e32 v76, 1, v234
	v_lshrrev_b32_e32 v77, 1, v234
	v_cndmask_b32_e64 v3, v72, v73, s[96:97]
	v_cmp_eq_u32_e64 s[96:97], 1, v234
	v_and_b32_e32 v78, 1, v234
	v_add_u32_e32 v79, 2, v77
	v_cndmask_b32_e64 v4, v72, v74, s[96:97]
	v_cndmask_b32_e64 v5, v72, v75, s[96:97]
	v_lshlrev_b32_e32 v76, 10, v76
	v_lshl_add_u32 v76, v233, 2, v76
	v_add_u32_e32 v8, s62, v76
	v_lshlrev_b32_e32 v76, 9, v234
	v_lshl_add_u32 v76, v233, 2, v76
	v_add_u32_e32 v9, s62, v76
	v_lshl_add_u32 v6, v79, 4, v233
	v_xor_b32_e32 v6, v6, v79
	v_lshlrev_b32_e32 v6, 4, v6
	v_lshl_add_u32 v6, v78, 3, v6
	v_add_u32_e32 v6, 0x2100, v6
	v_lshl_add_u32 v7, v78, 4, v233
	v_xor_b32_e32 v7, v7, v78
	v_lshlrev_b32_e32 v7, 4, v7
	v_lshl_add_u32 v7, v77, 3, v7
	v_add_u32_e32 v7, 0x2100, v7
	v_lshlrev_b32_e32 v0, 4, v233
	v_lshl_add_u32 v0, v78, 8, v0
	v_lshl_add_u32 v0, v77, 3, v0
	v_add_u32_e32 v0, 0x1000, v0
	v_lshlrev_b32_e32 v10, 4, v233
	v_lshl_add_u32 v10, v79, 8, v10
	v_lshl_add_u32 v10, v78, 3, v10
	v_add_u32_e32 v10, 0x1000, v10
	v_add_u32_e32 v232, 48, v224
	v_and_b32_e32 v232, 63, v232
	v_lshlrev_b32_e32 v232, 2, v232
.Lmy_ck_nz:
	s_mov_b32 s100, 0xe000
	s_cmp_eq_u32 s23, 0
	s_cselect_b32 s100, 0x1c000, s100
	s_mov_b32 s101, 0x12e00
	s_cselect_b32 s101, 0x22100, s101
	s_lshl_b32 s96, s23, 13
	s_add_i32 s97, s96, 0x18000
	s_add_i32 s96, s96, 0xa000
	v_add_u32_e32 v225, s100, v1
	v_add_u32_e32 v236, s100, v0
	v_add_u32_e32 v34, s100, v10
	v_add_u32_e32 v226, s100, v2
	v_add_u32_e32 v227, s100, v3
	v_add_u32_e32 v228, s100, v4
	v_add_u32_e32 v229, s100, v5
	v_add_u32_e32 v237, s100, v6
	v_add_u32_e32 v238, s100, v7
	v_add_u32_e32 v230, s96, v8
	v_add_u32_e32 v239, s96, v9
	v_add_u32_e32 v231, s97, v8
	v_add_u32_e32 v26, s101, v1
	v_add_u32_e32 v27, s101, v0
	v_add_u32_e32 v35, s101, v10
	v_add_u32_e32 v28, s101, v2
	v_add_u32_e32 v29, s101, v3
	v_add_u32_e32 v30, s101, v4
	v_add_u32_e32 v31, s101, v5
	v_add_u32_e32 v32, s101, v6
	v_add_u32_e32 v33, s101, v7
	s_cmp_eq_u32 s25, 1
	s_cbranch_scc1 .Lmy_f_skippro
	ds_read_b64 v[80:81], v237
	ds_read_b64 v[82:83], v238
	ds_read_b32 v36, v239
	ds_read_b32 v37, v239 offset:256
	ds_read_b128 v[88:91], v225
	ds_read_b128 v[92:95], v225 offset:1024
	ds_read_b128 v[96:99], v225 offset:2048
	ds_read_b128 v[100:103], v225 offset:3072
	ds_read_b32 v104, v227 offset:4
	ds_read_b32 v105, v227 offset:76
	ds_read_b64 v[106:107], v227 offset:8
	ds_read_b64 v[108:109], v227 offset:40
	ds_read_b32 v126, v229 offset:4
	ds_read_b32 v127, v229 offset:76
	ds_read_b64 v[128:129], v229 offset:8
	ds_read_b64 v[130:131], v229 offset:40
	ds_read_b64 v[110:111], v228
	ds_read_b64 v[112:113], v228 offset:32
	ds_read_b64 v[114:115], v228 offset:64
	ds_read_b64 v[116:117], v228 offset:96
	ds_read_b64 v[118:119], v228 offset:8
	ds_read_b64 v[120:121], v228 offset:40
	ds_read_b64 v[122:123], v228 offset:72
	ds_read_b64 v[124:125], v228 offset:104
	s_waitcnt lgkmcnt(15)
	v_mfma_f32_16x16x4_f32 v[240:243], v80, v36, 0
	v_mfma_f32_16x16x4_f32 v[240:243], v81, v37, v[240:243]
.Lmy_f_skippro:
	v_mfma_f32_16x16x4_f32 v[240:243], v88, v208, v[240:243]
	ds_read_b64 v[186:187], v34
	ds_read_b64 v[190:191], v34 offset:1024
	v_mfma_f32_16x16x4_f32 v[244:247], v89, v209, 0
	ds_read_b64 v[194:195], v34 offset:2048
	ds_read_b64 v[198:199], v34 offset:3072
	v_mfma_f32_16x16x4_f32 v[240:243], v90, v210, v[240:243]
	ds_read_b64 v[184:185], v236
	ds_read_b64 v[188:189], v236 offset:1024
	ds_read_b64 v[132:133], v237 offset:9984
	v_mfma_f32_16x16x4_f32 v[244:247], v91, v211, v[244:247]
	ds_read_b64 v[134:135], v238 offset:9984
	ds_read_b64 v[192:193], v236 offset:2048
	ds_read_b64 v[196:197], v236 offset:3072
	v_mfma_f32_16x16x4_f32 v[240:243], v92, v212, v[240:243]
	ds_read_b32 v38, v239 offset:2048
	ds_read_b32 v39, v239 offset:2304
	ds_read_b128 v[140:143], v225 offset:9984
	v_mfma_f32_16x16x4_f32 v[244:247], v93, v213, v[244:247]
	ds_read_b128 v[144:147], v225 offset:11008
	ds_read_b128 v[148:151], v225 offset:12032
	ds_read_b128 v[152:155], v225 offset:13056
	v_mfma_f32_16x16x4_f32 v[240:243], v94, v214, v[240:243]
	ds_read_b32 v156, v227 offset:9988
	ds_read_b32 v157, v227 offset:10060
	v_mfma_f32_16x16x4_f32 v[244:247], v95, v215, v[244:247]
	ds_read_b64 v[158:159], v227 offset:9992
	ds_read_b64 v[160:161], v227 offset:10024
	v_mfma_f32_16x16x4_f32 v[240:243], v96, v216, v[240:243]
	ds_read_b32 v178, v229 offset:9988
	ds_read_b32 v179, v229 offset:10060
	v_mfma_f32_16x16x4_f32 v[244:247], v97, v217, v[244:247]
	ds_read_b64 v[180:181], v229 offset:9992
	ds_read_b64 v[182:183], v229 offset:10024
	v_mfma_f32_16x16x4_f32 v[240:243], v98, v218, v[240:243]
	ds_read_b64 v[162:163], v228 offset:9984
	ds_read_b64 v[164:165], v228 offset:10016
	v_mfma_f32_16x16x4_f32 v[244:247], v99, v219, v[244:247]
	ds_read_b64 v[166:167], v228 offset:10048
	ds_read_b64 v[168:169], v228 offset:10080
	v_mfma_f32_16x16x4_f32 v[240:243], v100, v220, v[240:243]
	ds_read_b64 v[170:171], v228 offset:9992
	ds_read_b64 v[172:173], v228 offset:10024
	v_mfma_f32_16x16x4_f32 v[244:247], v101, v221, v[244:247]
	ds_read_b64 v[174:175], v228 offset:10056
	ds_read_b64 v[176:177], v228 offset:10088
	v_mfma_f32_16x16x4_f32 v[240:243], v102, v222, v[240:243]
	v_mfma_f32_16x16x4_f32 v[244:247], v103, v223, v[244:247]
	s_waitcnt lgkmcnt(15)
	v_mfma_f32_16x16x4_f32 v[208:211], v186, v36, v[208:211]
	s_nop 2
	v_pk_add_f32 v[240:241], v[240:241], v[244:245]
	v_pk_add_f32 v[242:243], v[242:243], v[246:247]
	v_fmac_f32_e32 v241, v104, v240
	v_mfma_f32_16x16x4_f32 v[212:215], v190, v36, v[212:215]
	v_pk_fma_f32 v[242:243], v[106:107], v[240:241], v[242:243] op_sel:[0,0,0] op_sel_hi:[1,0,1]
	v_pk_fma_f32 v[242:243], v[108:109], v[240:241], v[242:243] op_sel:[0,1,0] op_sel_hi:[1,1,1]
	v_fmac_f32_e32 v243, v105, v242
	v_mfma_f32_16x16x4_f32 v[216:219], v194, v36, v[216:219]
	ds_bpermute_b32 v204, v232, v240
	ds_bpermute_b32 v205, v232, v241
	ds_bpermute_b32 v206, v232, v242
	v_mfma_f32_16x16x4_f32 v[72:75], v132, v38, 0
	ds_bpermute_b32 v207, v232, v243
	s_waitcnt lgkmcnt(2)
	v_pk_fma_f32 v[240:241], v[110:111], v[204:205], v[240:241] op_sel:[0,0,0] op_sel_hi:[1,0,1]
	v_pk_fma_f32 v[240:241], v[112:113], v[204:205], v[240:241] op_sel:[0,1,0] op_sel_hi:[1,1,1]
	v_mfma_f32_16x16x4_f32 v[72:75], v133, v39, v[72:75]
	s_waitcnt lgkmcnt(0)
	v_pk_fma_f32 v[240:241], v[114:115], v[206:207], v[240:241] op_sel:[0,0,0] op_sel_hi:[1,0,1]
	v_pk_fma_f32 v[240:241], v[116:117], v[206:207], v[240:241] op_sel:[0,1,0] op_sel_hi:[1,1,1]
	v_pk_fma_f32 v[242:243], v[118:119], v[204:205], v[242:243] op_sel:[0,0,0] op_sel_hi:[1,0,1]
	v_mfma_f32_16x16x4_f32 v[220:223], v198, v36, v[220:223]
	v_pk_fma_f32 v[242:243], v[120:121], v[204:205], v[242:243] op_sel:[0,1,0] op_sel_hi:[1,1,1]
	v_pk_fma_f32 v[242:243], v[122:123], v[206:207], v[242:243] op_sel:[0,0,0] op_sel_hi:[1,0,1]
	v_pk_fma_f32 v[242:243], v[124:125], v[206:207], v[242:243] op_sel:[0,1,0] op_sel_hi:[1,1,1]
	v_mfma_f32_16x16x4_f32 v[208:211], v187, v37, v[208:211]
	v_fmac_f32_e32 v241, v126, v240
	v_pk_fma_f32 v[242:243], v[128:129], v[240:241], v[242:243] op_sel:[0,0,0] op_sel_hi:[1,0,1]
	v_pk_fma_f32 v[242:243], v[130:131], v[240:241], v[242:243] op_sel:[0,1,0] op_sel_hi:[1,1,1]
	v_mfma_f32_16x16x4_f32 v[212:215], v191, v37, v[212:215]
	v_fmac_f32_e32 v243, v127, v242
	v_mov_b32_e32 v252, v240
	v_mov_b32_e32 v253, v241
	v_mfma_f32_16x16x4_f32 v[216:219], v195, v37, v[216:219]
	v_mov_b32_e32 v254, v242
	v_mov_b32_e32 v255, v243
	s_nop 0
	v_permlane32_swap_b32_e32 v252, v254
	v_mfma_f32_16x16x4_f32 v[220:223], v199, v37, v[220:223]
	v_permlane32_swap_b32_e32 v253, v255
	v_mfma_f32_16x16x4_f32 v[208:211], v184, v252, v[208:211]
	ds_read_b128 v[88:91], v226
	v_mfma_f32_16x16x4_f32 v[212:215], v188, v252, v[212:215]
	ds_read_b128 v[92:95], v226 offset:64
	v_mfma_f32_16x16x4_f32 v[216:219], v192, v252, v[216:219]
	ds_read_b128 v[96:99], v226 offset:128
	v_mfma_f32_16x16x4_f32 v[220:223], v196, v252, v[220:223]
	ds_read_b128 v[100:103], v226 offset:192
	v_mfma_f32_16x16x4_f32 v[208:211], v185, v253, v[208:211]
	v_mfma_f32_16x16x4_f32 v[212:215], v189, v253, v[212:215]
	v_mfma_f32_16x16x4_f32 v[216:219], v193, v253, v[216:219]
	v_mfma_f32_16x16x4_f32 v[220:223], v197, v253, v[220:223]
	v_mfma_f32_16x16x4_f32 v[248:251], v82, v252, v[240:243]
	v_mfma_f32_16x16x4_f32 v[248:251], v83, v253, v[248:251]
	s_waitcnt lgkmcnt(3)
	v_pk_mul_f32 v[208:209], v[208:209], v[88:89]
	v_pk_mul_f32 v[210:211], v[210:211], v[90:91]
	s_nop 0
	v_mfma_f32_16x16x4_f32 v[72:75], v140, v208, v[72:75]
	s_waitcnt lgkmcnt(2)
	v_pk_mul_f32 v[212:213], v[212:213], v[92:93]
	v_mfma_f32_16x16x4_f32 v[244:247], v141, v209, 0
	v_pk_mul_f32 v[214:215], v[214:215], v[94:95]
	v_mfma_f32_16x16x4_f32 v[72:75], v142, v210, v[72:75]
	s_waitcnt lgkmcnt(1)
	v_pk_mul_f32 v[216:217], v[216:217], v[96:97]
	v_mfma_f32_16x16x4_f32 v[244:247], v143, v211, v[244:247]
	v_pk_mul_f32 v[218:219], v[218:219], v[98:99]
	v_mfma_f32_16x16x4_f32 v[72:75], v144, v212, v[72:75]
	s_waitcnt lgkmcnt(0)
	v_pk_mul_f32 v[220:221], v[220:221], v[100:101]
	v_mfma_f32_16x16x4_f32 v[244:247], v145, v213, v[244:247]
	v_pk_mul_f32 v[222:223], v[222:223], v[102:103]
	v_mfma_f32_16x16x4_f32 v[72:75], v146, v214, v[72:75]
	s_mov_b64 exec, s[98:99]
	ds_write_b32 v231, v248
	ds_write_b32 v231, v249 offset:256
	ds_write_b32 v231, v250 offset:512
	ds_write_b32 v231, v251 offset:768
	s_mov_b64 exec, -1
	ds_read_b64 v[186:187], v34 offset:9984
	ds_read_b64 v[190:191], v34 offset:11008
	v_mfma_f32_16x16x4_f32 v[244:247], v147, v215, v[244:247]
	ds_read_b64 v[194:195], v34 offset:12032
	ds_read_b64 v[198:199], v34 offset:13056
	v_mfma_f32_16x16x4_f32 v[72:75], v148, v216, v[72:75]
	ds_read_b64 v[184:185], v236 offset:9984
	ds_read_b64 v[188:189], v236 offset:11008
	ds_read_b64 v[80:81], v32
	v_mfma_f32_16x16x4_f32 v[244:247], v149, v217, v[244:247]
	ds_read_b64 v[82:83], v33
	ds_read_b32 v36, v239 offset:4096
	ds_read_b64 v[192:193], v236 offset:12032
	v_mfma_f32_16x16x4_f32 v[72:75], v150, v218, v[72:75]
	ds_read_b64 v[196:197], v236 offset:13056
	ds_read_b32 v37, v239 offset:4352
	ds_read_b128 v[88:91], v26
	v_mfma_f32_16x16x4_f32 v[244:247], v151, v219, v[244:247]
	ds_read_b128 v[92:95], v26 offset:1024
	ds_read_b128 v[96:99], v26 offset:2048
	ds_read_b128 v[100:103], v26 offset:3072
	v_mfma_f32_16x16x4_f32 v[72:75], v152, v220, v[72:75]
	ds_read_b32 v104, v29 offset:4
	ds_read_b32 v105, v29 offset:76
	ds_read_b64 v[106:107], v29 offset:8
	v_mfma_f32_16x16x4_f32 v[244:247], v153, v221, v[244:247]
	ds_read_b64 v[108:109], v29 offset:40
	ds_read_b32 v126, v31 offset:4
	ds_read_b32 v127, v31 offset:76
	v_mfma_f32_16x16x4_f32 v[72:75], v154, v222, v[72:75]
	ds_read_b64 v[128:129], v31 offset:8
	ds_read_b64 v[130:131], v31 offset:40
	ds_read_b64 v[110:111], v30
	v_mfma_f32_16x16x4_f32 v[244:247], v155, v223, v[244:247]
	ds_read_b64 v[112:113], v30 offset:32
	ds_read_b64 v[114:115], v30 offset:64
	ds_read_b64 v[116:117], v30 offset:96
	ds_read_b64 v[118:119], v30 offset:8
	ds_read_b64 v[120:121], v30 offset:40
	ds_read_b64 v[122:123], v30 offset:72
	ds_read_b64 v[124:125], v30 offset:104
	s_waitcnt lgkmcnt(15)
	v_mfma_f32_16x16x4_f32 v[208:211], v186, v38, v[208:211]
	s_nop 1
	v_pk_add_f32 v[72:73], v[72:73], v[244:245]
	v_pk_add_f32 v[74:75], v[74:75], v[246:247]
	v_fmac_f32_e32 v73, v156, v72
	v_mfma_f32_16x16x4_f32 v[212:215], v190, v38, v[212:215]
	v_pk_fma_f32 v[74:75], v[158:159], v[72:73], v[74:75] op_sel:[0,0,0] op_sel_hi:[1,0,1]
	v_pk_fma_f32 v[74:75], v[160:161], v[72:73], v[74:75] op_sel:[0,1,0] op_sel_hi:[1,1,1]
	v_fmac_f32_e32 v75, v157, v74
	v_mfma_f32_16x16x4_f32 v[216:219], v194, v38, v[216:219]
	ds_bpermute_b32 v204, v232, v72
	ds_bpermute_b32 v205, v232, v73
	ds_bpermute_b32 v206, v232, v74
	v_mfma_f32_16x16x4_f32 v[240:243], v80, v36, 0
	ds_bpermute_b32 v207, v232, v75
	s_waitcnt lgkmcnt(2)
	v_pk_fma_f32 v[72:73], v[162:163], v[204:205], v[72:73] op_sel:[0,0,0] op_sel_hi:[1,0,1]
	v_pk_fma_f32 v[72:73], v[164:165], v[204:205], v[72:73] op_sel:[0,1,0] op_sel_hi:[1,1,1]
	v_mfma_f32_16x16x4_f32 v[240:243], v81, v37, v[240:243]
	s_waitcnt lgkmcnt(0)
	v_pk_fma_f32 v[72:73], v[166:167], v[206:207], v[72:73] op_sel:[0,0,0] op_sel_hi:[1,0,1]
	v_pk_fma_f32 v[72:73], v[168:169], v[206:207], v[72:73] op_sel:[0,1,0] op_sel_hi:[1,1,1]
	v_pk_fma_f32 v[74:75], v[170:171], v[204:205], v[74:75] op_sel:[0,0,0] op_sel_hi:[1,0,1]
	v_mfma_f32_16x16x4_f32 v[220:223], v198, v38, v[220:223]
	v_pk_fma_f32 v[74:75], v[172:173], v[204:205], v[74:75] op_sel:[0,1,0] op_sel_hi:[1,1,1]
	v_pk_fma_f32 v[74:75], v[174:175], v[206:207], v[74:75] op_sel:[0,0,0] op_sel_hi:[1,0,1]
	v_pk_fma_f32 v[74:75], v[176:177], v[206:207], v[74:75] op_sel:[0,1,0] op_sel_hi:[1,1,1]
	v_mfma_f32_16x16x4_f32 v[208:211], v187, v39, v[208:211]
	v_fmac_f32_e32 v73, v178, v72
	v_pk_fma_f32 v[74:75], v[180:181], v[72:73], v[74:75] op_sel:[0,0,0] op_sel_hi:[1,0,1]
	v_pk_fma_f32 v[74:75], v[182:183], v[72:73], v[74:75] op_sel:[0,1,0] op_sel_hi:[1,1,1]
	v_mfma_f32_16x16x4_f32 v[212:215], v191, v39, v[212:215]
	v_fmac_f32_e32 v75, v179, v74
	v_mov_b32_e32 v252, v72
	v_mov_b32_e32 v253, v73
	v_mfma_f32_16x16x4_f32 v[216:219], v195, v39, v[216:219]
	v_mov_b32_e32 v254, v74
	v_mov_b32_e32 v255, v75
	s_nop 0
	v_permlane32_swap_b32_e32 v252, v254
	v_mfma_f32_16x16x4_f32 v[220:223], v199, v39, v[220:223]
	v_permlane32_swap_b32_e32 v253, v255
	v_mfma_f32_16x16x4_f32 v[208:211], v184, v252, v[208:211]
	ds_read_b128 v[140:143], v226 offset:9984
	v_mfma_f32_16x16x4_f32 v[212:215], v188, v252, v[212:215]
	ds_read_b128 v[144:147], v226 offset:10048
	v_mfma_f32_16x16x4_f32 v[216:219], v192, v252, v[216:219]
	ds_read_b128 v[148:151], v226 offset:10112
	v_mfma_f32_16x16x4_f32 v[220:223], v196, v252, v[220:223]
	ds_read_b128 v[152:155], v226 offset:10176
	v_mfma_f32_16x16x4_f32 v[208:211], v185, v253, v[208:211]
	v_mfma_f32_16x16x4_f32 v[212:215], v189, v253, v[212:215]
	v_mfma_f32_16x16x4_f32 v[216:219], v193, v253, v[216:219]
	v_mfma_f32_16x16x4_f32 v[220:223], v197, v253, v[220:223]
	v_mfma_f32_16x16x4_f32 v[248:251], v134, v252, v[72:75]
	v_mfma_f32_16x16x4_f32 v[248:251], v135, v253, v[248:251]
	s_waitcnt lgkmcnt(3)
	v_pk_mul_f32 v[208:209], v[208:209], v[140:141]
	v_pk_mul_f32 v[210:211], v[210:211], v[142:143]
	s_nop 0
	v_mfma_f32_16x16x4_f32 v[240:243], v88, v208, v[240:243]
	s_waitcnt lgkmcnt(2)
	v_pk_mul_f32 v[212:213], v[212:213], v[144:145]
	v_mfma_f32_16x16x4_f32 v[244:247], v89, v209, 0
	v_pk_mul_f32 v[214:215], v[214:215], v[146:147]
	v_mfma_f32_16x16x4_f32 v[240:243], v90, v210, v[240:243]
	s_waitcnt lgkmcnt(1)
	v_pk_mul_f32 v[216:217], v[216:217], v[148:149]
	v_mfma_f32_16x16x4_f32 v[244:247], v91, v211, v[244:247]
	v_pk_mul_f32 v[218:219], v[218:219], v[150:151]
	v_mfma_f32_16x16x4_f32 v[240:243], v92, v212, v[240:243]
	s_waitcnt lgkmcnt(0)
	v_pk_mul_f32 v[220:221], v[220:221], v[152:153]
	v_mfma_f32_16x16x4_f32 v[244:247], v93, v213, v[244:247]
	v_pk_mul_f32 v[222:223], v[222:223], v[154:155]
	v_mfma_f32_16x16x4_f32 v[240:243], v94, v214, v[240:243]
	s_mov_b64 exec, s[98:99]
	ds_write_b32 v231, v248 offset:2048
	ds_write_b32 v231, v249 offset:2304
	ds_write_b32 v231, v250 offset:2560
	ds_write_b32 v231, v251 offset:2816
	s_mov_b64 exec, -1
	ds_read_b64 v[186:187], v35
	ds_read_b64 v[190:191], v35 offset:1024
	v_mfma_f32_16x16x4_f32 v[244:247], v95, v215, v[244:247]
	ds_read_b64 v[194:195], v35 offset:2048
	ds_read_b64 v[198:199], v35 offset:3072
	v_mfma_f32_16x16x4_f32 v[240:243], v96, v216, v[240:243]
	ds_read_b64 v[184:185], v27
	ds_read_b64 v[188:189], v27 offset:1024
	ds_read_b64 v[132:133], v32 offset:9984
	v_mfma_f32_16x16x4_f32 v[244:247], v97, v217, v[244:247]
	ds_read_b64 v[134:135], v33 offset:9984
	ds_read_b32 v38, v239 offset:6144
	ds_read_b64 v[192:193], v27 offset:2048
	v_mfma_f32_16x16x4_f32 v[240:243], v98, v218, v[240:243]
	ds_read_b64 v[196:197], v27 offset:3072
	ds_read_b32 v39, v239 offset:6400
	ds_read_b128 v[140:143], v26 offset:9984
	v_mfma_f32_16x16x4_f32 v[244:247], v99, v219, v[244:247]
	ds_read_b128 v[144:147], v26 offset:11008
	ds_read_b128 v[148:151], v26 offset:12032
	ds_read_b128 v[152:155], v26 offset:13056
	v_mfma_f32_16x16x4_f32 v[240:243], v100, v220, v[240:243]
	ds_read_b32 v156, v29 offset:9988
	ds_read_b32 v157, v29 offset:10060
	ds_read_b64 v[158:159], v29 offset:9992
	v_mfma_f32_16x16x4_f32 v[244:247], v101, v221, v[244:247]
	ds_read_b64 v[160:161], v29 offset:10024
	ds_read_b32 v178, v31 offset:9988
	ds_read_b32 v179, v31 offset:10060
	v_mfma_f32_16x16x4_f32 v[240:243], v102, v222, v[240:243]
	ds_read_b64 v[180:181], v31 offset:9992
	ds_read_b64 v[182:183], v31 offset:10024
	ds_read_b64 v[162:163], v30 offset:9984
	v_mfma_f32_16x16x4_f32 v[244:247], v103, v223, v[244:247]
	ds_read_b64 v[164:165], v30 offset:10016
	ds_read_b64 v[166:167], v30 offset:10048
	ds_read_b64 v[168:169], v30 offset:10080
	ds_read_b64 v[170:171], v30 offset:9992
	ds_read_b64 v[172:173], v30 offset:10024
	ds_read_b64 v[174:175], v30 offset:10056
	ds_read_b64 v[176:177], v30 offset:10088
	s_waitcnt lgkmcnt(15)
	v_mfma_f32_16x16x4_f32 v[208:211], v186, v36, v[208:211]
	s_nop 1
	v_pk_add_f32 v[240:241], v[240:241], v[244:245]
	v_pk_add_f32 v[242:243], v[242:243], v[246:247]
	v_fmac_f32_e32 v241, v104, v240
	v_mfma_f32_16x16x4_f32 v[212:215], v190, v36, v[212:215]
	v_pk_fma_f32 v[242:243], v[106:107], v[240:241], v[242:243] op_sel:[0,0,0] op_sel_hi:[1,0,1]
	v_pk_fma_f32 v[242:243], v[108:109], v[240:241], v[242:243] op_sel:[0,1,0] op_sel_hi:[1,1,1]
	v_fmac_f32_e32 v243, v105, v242
	v_mfma_f32_16x16x4_f32 v[216:219], v194, v36, v[216:219]
	ds_bpermute_b32 v204, v232, v240
	ds_bpermute_b32 v205, v232, v241
	ds_bpermute_b32 v206, v232, v242
	v_mfma_f32_16x16x4_f32 v[72:75], v132, v38, 0
	ds_bpermute_b32 v207, v232, v243
	s_waitcnt lgkmcnt(2)
	v_pk_fma_f32 v[240:241], v[110:111], v[204:205], v[240:241] op_sel:[0,0,0] op_sel_hi:[1,0,1]
	v_pk_fma_f32 v[240:241], v[112:113], v[204:205], v[240:241] op_sel:[0,1,0] op_sel_hi:[1,1,1]
	v_mfma_f32_16x16x4_f32 v[72:75], v133, v39, v[72:75]
	s_waitcnt lgkmcnt(0)
	v_pk_fma_f32 v[240:241], v[114:115], v[206:207], v[240:241] op_sel:[0,0,0] op_sel_hi:[1,0,1]
	v_pk_fma_f32 v[240:241], v[116:117], v[206:207], v[240:241] op_sel:[0,1,0] op_sel_hi:[1,1,1]
	v_pk_fma_f32 v[242:243], v[118:119], v[204:205], v[242:243] op_sel:[0,0,0] op_sel_hi:[1,0,1]
	v_mfma_f32_16x16x4_f32 v[220:223], v198, v36, v[220:223]
	v_pk_fma_f32 v[242:243], v[120:121], v[204:205], v[242:243] op_sel:[0,1,0] op_sel_hi:[1,1,1]
	v_pk_fma_f32 v[242:243], v[122:123], v[206:207], v[242:243] op_sel:[0,0,0] op_sel_hi:[1,0,1]
	v_pk_fma_f32 v[242:243], v[124:125], v[206:207], v[242:243] op_sel:[0,1,0] op_sel_hi:[1,1,1]
	v_mfma_f32_16x16x4_f32 v[208:211], v187, v37, v[208:211]
	v_fmac_f32_e32 v241, v126, v240
	v_pk_fma_f32 v[242:243], v[128:129], v[240:241], v[242:243] op_sel:[0,0,0] op_sel_hi:[1,0,1]
	v_pk_fma_f32 v[242:243], v[130:131], v[240:241], v[242:243] op_sel:[0,1,0] op_sel_hi:[1,1,1]
	v_mfma_f32_16x16x4_f32 v[212:215], v191, v37, v[212:215]
	v_fmac_f32_e32 v243, v127, v242
	v_mov_b32_e32 v252, v240
	v_mov_b32_e32 v253, v241
	v_mfma_f32_16x16x4_f32 v[216:219], v195, v37, v[216:219]
	v_mov_b32_e32 v254, v242
	v_mov_b32_e32 v255, v243
	s_nop 0
	v_permlane32_swap_b32_e32 v252, v254
	v_mfma_f32_16x16x4_f32 v[220:223], v199, v37, v[220:223]
	v_permlane32_swap_b32_e32 v253, v255
	v_mfma_f32_16x16x4_f32 v[208:211], v184, v252, v[208:211]
	ds_read_b128 v[88:91], v28
	v_mfma_f32_16x16x4_f32 v[212:215], v188, v252, v[212:215]
	ds_read_b128 v[92:95], v28 offset:64
	v_mfma_f32_16x16x4_f32 v[216:219], v192, v252, v[216:219]
	ds_read_b128 v[96:99], v28 offset:128
	v_mfma_f32_16x16x4_f32 v[220:223], v196, v252, v[220:223]
	ds_read_b128 v[100:103], v28 offset:192
	v_mfma_f32_16x16x4_f32 v[208:211], v185, v253, v[208:211]
	v_mfma_f32_16x16x4_f32 v[212:215], v189, v253, v[212:215]
	v_mfma_f32_16x16x4_f32 v[216:219], v193, v253, v[216:219]
	v_mfma_f32_16x16x4_f32 v[220:223], v197, v253, v[220:223]
	v_mfma_f32_16x16x4_f32 v[248:251], v82, v252, v[240:243]
	v_mfma_f32_16x16x4_f32 v[248:251], v83, v253, v[248:251]
	s_waitcnt lgkmcnt(3)
	v_pk_mul_f32 v[208:209], v[208:209], v[88:89]
	v_pk_mul_f32 v[210:211], v[210:211], v[90:91]
	s_nop 0
	v_mfma_f32_16x16x4_f32 v[72:75], v140, v208, v[72:75]
	s_waitcnt lgkmcnt(2)
	v_pk_mul_f32 v[212:213], v[212:213], v[92:93]
	v_mfma_f32_16x16x4_f32 v[244:247], v141, v209, 0
	v_pk_mul_f32 v[214:215], v[214:215], v[94:95]
	v_mfma_f32_16x16x4_f32 v[72:75], v142, v210, v[72:75]
	s_waitcnt lgkmcnt(1)
	v_pk_mul_f32 v[216:217], v[216:217], v[96:97]
	v_mfma_f32_16x16x4_f32 v[244:247], v143, v211, v[244:247]
	v_pk_mul_f32 v[218:219], v[218:219], v[98:99]
	v_mfma_f32_16x16x4_f32 v[72:75], v144, v212, v[72:75]
	s_waitcnt lgkmcnt(0)
	v_pk_mul_f32 v[220:221], v[220:221], v[100:101]
	v_mfma_f32_16x16x4_f32 v[244:247], v145, v213, v[244:247]
	v_pk_mul_f32 v[222:223], v[222:223], v[102:103]
	v_mfma_f32_16x16x4_f32 v[72:75], v146, v214, v[72:75]
	s_mov_b64 exec, s[98:99]
	ds_write_b32 v231, v248 offset:4096
	ds_write_b32 v231, v249 offset:4352
	ds_write_b32 v231, v250 offset:4608
	ds_write_b32 v231, v251 offset:4864
	s_mov_b64 exec, -1
	ds_read_b64 v[186:187], v35 offset:9984
	ds_read_b64 v[190:191], v35 offset:11008
	v_mfma_f32_16x16x4_f32 v[244:247], v147, v215, v[244:247]
	ds_read_b64 v[194:195], v35 offset:12032
	ds_read_b64 v[198:199], v35 offset:13056
	v_mfma_f32_16x16x4_f32 v[72:75], v148, v216, v[72:75]
	ds_read_b64 v[184:185], v27 offset:9984
	ds_read_b64 v[188:189], v27 offset:11008
	v_mfma_f32_16x16x4_f32 v[244:247], v149, v217, v[244:247]
	ds_read_b64 v[192:193], v27 offset:12032
	ds_read_b64 v[196:197], v27 offset:13056
	v_mfma_f32_16x16x4_f32 v[72:75], v150, v218, v[72:75]
	v_mfma_f32_16x16x4_f32 v[244:247], v151, v219, v[244:247]
	v_mfma_f32_16x16x4_f32 v[72:75], v152, v220, v[72:75]
	v_mfma_f32_16x16x4_f32 v[244:247], v153, v221, v[244:247]
	v_mfma_f32_16x16x4_f32 v[72:75], v154, v222, v[72:75]
	v_mfma_f32_16x16x4_f32 v[244:247], v155, v223, v[244:247]
	ds_read_b32 v19, v18
	s_waitcnt lgkmcnt(8)
	v_mfma_f32_16x16x4_f32 v[208:211], v186, v38, v[208:211]
	s_nop 7
	v_pk_add_f32 v[72:73], v[72:73], v[244:245]
	v_pk_add_f32 v[74:75], v[74:75], v[246:247]
	v_fmac_f32_e32 v73, v156, v72
	s_waitcnt lgkmcnt(7)
	v_mfma_f32_16x16x4_f32 v[212:215], v190, v38, v[212:215]
	v_pk_fma_f32 v[74:75], v[158:159], v[72:73], v[74:75] op_sel:[0,0,0] op_sel_hi:[1,0,1]
	v_pk_fma_f32 v[74:75], v[160:161], v[72:73], v[74:75] op_sel:[0,1,0] op_sel_hi:[1,1,1]
	v_fmac_f32_e32 v75, v157, v74
	s_waitcnt lgkmcnt(6)
	v_mfma_f32_16x16x4_f32 v[216:219], v194, v38, v[216:219]
	ds_bpermute_b32 v204, v232, v72
	ds_bpermute_b32 v205, v232, v73
	ds_bpermute_b32 v206, v232, v74
	s_waitcnt lgkmcnt(8)
	v_mfma_f32_16x16x4_f32 v[220:223], v198, v38, v[220:223]
	ds_bpermute_b32 v207, v232, v75
	s_waitcnt lgkmcnt(2)
	v_pk_fma_f32 v[72:73], v[162:163], v[204:205], v[72:73] op_sel:[0,0,0] op_sel_hi:[1,0,1]
	v_pk_fma_f32 v[72:73], v[164:165], v[204:205], v[72:73] op_sel:[0,1,0] op_sel_hi:[1,1,1]
	v_mfma_f32_16x16x4_f32 v[208:211], v187, v39, v[208:211]
	s_waitcnt lgkmcnt(0)
	v_pk_fma_f32 v[72:73], v[166:167], v[206:207], v[72:73] op_sel:[0,0,0] op_sel_hi:[1,0,1]
	v_pk_fma_f32 v[72:73], v[168:169], v[206:207], v[72:73] op_sel:[0,1,0] op_sel_hi:[1,1,1]
	v_pk_fma_f32 v[74:75], v[170:171], v[204:205], v[74:75] op_sel:[0,0,0] op_sel_hi:[1,0,1]
	v_mfma_f32_16x16x4_f32 v[212:215], v191, v39, v[212:215]
	v_pk_fma_f32 v[74:75], v[172:173], v[204:205], v[74:75] op_sel:[0,1,0] op_sel_hi:[1,1,1]
	v_pk_fma_f32 v[74:75], v[174:175], v[206:207], v[74:75] op_sel:[0,0,0] op_sel_hi:[1,0,1]
	v_pk_fma_f32 v[74:75], v[176:177], v[206:207], v[74:75] op_sel:[0,1,0] op_sel_hi:[1,1,1]
	v_mfma_f32_16x16x4_f32 v[216:219], v195, v39, v[216:219]
	v_fmac_f32_e32 v73, v178, v72
	v_pk_fma_f32 v[74:75], v[180:181], v[72:73], v[74:75] op_sel:[0,0,0] op_sel_hi:[1,0,1]
	v_pk_fma_f32 v[74:75], v[182:183], v[72:73], v[74:75] op_sel:[0,1,0] op_sel_hi:[1,1,1]
	v_mfma_f32_16x16x4_f32 v[220:223], v199, v39, v[220:223]
	v_fmac_f32_e32 v75, v179, v74
	v_mov_b32_e32 v252, v72
	v_mov_b32_e32 v253, v73
	v_mov_b32_e32 v254, v74
	v_mov_b32_e32 v255, v75
	s_nop 0
	v_permlane32_swap_b32_e32 v252, v254
	v_permlane32_swap_b32_e32 v253, v255
	v_readfirstlane_b32 s96, v19
	s_cmp_eq_u32 s96, s22
	s_cselect_b32 s25, 1, 0
	s_cbranch_scc0 .Lmy_f_nopf
	v_mfma_f32_16x16x4_f32 v[208:211], v184, v252, v[208:211]
	ds_read_b128 v[140:143], v28 offset:9984
	s_mov_b32 s100, 0x1c000
	s_cmp_eq_u32 s23, 0
	s_cselect_b32 s100, 0xe000, s100
	s_xor_b32 s96, s23, 1
	s_lshl_b32 s96, s96, 13
	s_add_i32 s96, s96, 0xa000
	v_add_u32_e32 v11, s100, v6
	v_add_u32_e32 v12, s100, v7
	v_mfma_f32_16x16x4_f32 v[212:215], v188, v252, v[212:215]
	ds_read_b128 v[144:147], v28 offset:10048
	v_add_u32_e32 v13, s100, v1
	v_add_u32_e32 v14, s100, v3
	v_add_u32_e32 v15, s100, v4
	v_mfma_f32_16x16x4_f32 v[216:219], v192, v252, v[216:219]
	ds_read_b128 v[148:151], v28 offset:10112
	v_add_u32_e32 v16, s100, v5
	v_add_u32_e32 v17, s96, v9
	ds_read_b128 v[88:91], v13
	v_mfma_f32_16x16x4_f32 v[220:223], v196, v252, v[220:223]
	ds_read_b128 v[152:155], v28 offset:10176
	ds_read_b128 v[92:95], v13 offset:1024
	ds_read_b128 v[96:99], v13 offset:2048
	ds_read_b128 v[100:103], v13 offset:3072
	v_mfma_f32_16x16x4_f32 v[208:211], v185, v253, v[208:211]
	ds_read_b32 v104, v14 offset:4
	ds_read_b32 v105, v14 offset:76
	ds_read_b64 v[106:107], v14 offset:8
	ds_read_b64 v[108:109], v14 offset:40
	v_mfma_f32_16x16x4_f32 v[212:215], v189, v253, v[212:215]
	ds_read_b32 v126, v16 offset:4
	ds_read_b32 v127, v16 offset:76
	ds_read_b64 v[128:129], v16 offset:8
	ds_read_b64 v[130:131], v16 offset:40
	v_mfma_f32_16x16x4_f32 v[216:219], v193, v253, v[216:219]
	ds_read_b64 v[110:111], v15
	ds_read_b64 v[112:113], v15 offset:32
	ds_read_b64 v[114:115], v15 offset:64
	ds_read_b64 v[116:117], v15 offset:96
	v_mfma_f32_16x16x4_f32 v[220:223], v197, v253, v[220:223]
	ds_read_b64 v[118:119], v15 offset:8
	ds_read_b64 v[120:121], v15 offset:40
	ds_read_b64 v[122:123], v15 offset:72
	ds_read_b64 v[124:125], v15 offset:104
	v_mfma_f32_16x16x4_f32 v[248:251], v134, v252, v[72:75]
	ds_read_b64 v[80:81], v11
	ds_read_b64 v[82:83], v12
	ds_read_b32 v36, v17
	ds_read_b32 v37, v17 offset:256
	v_mfma_f32_16x16x4_f32 v[248:251], v135, v253, v[248:251]
	s_waitcnt lgkmcnt(1)
	v_mfma_f32_16x16x4_f32 v[240:243], v80, v36, 0
	s_waitcnt lgkmcnt(0)
	v_mfma_f32_16x16x4_f32 v[240:243], v81, v37, v[240:243]
	s_branch .Lmy_f_pfjoin
.Lmy_f_nopf:
	s_waitcnt lgkmcnt(0)
	v_mfma_f32_16x16x4_f32 v[208:211], v184, v252, v[208:211]
	ds_read_b128 v[140:143], v28 offset:9984
	v_mfma_f32_16x16x4_f32 v[212:215], v188, v252, v[212:215]
	ds_read_b128 v[144:147], v28 offset:10048
	v_mfma_f32_16x16x4_f32 v[216:219], v192, v252, v[216:219]
	ds_read_b128 v[148:151], v28 offset:10112
	v_mfma_f32_16x16x4_f32 v[220:223], v196, v252, v[220:223]
	ds_read_b128 v[152:155], v28 offset:10176
	v_mfma_f32_16x16x4_f32 v[208:211], v185, v253, v[208:211]
	v_mfma_f32_16x16x4_f32 v[212:215], v189, v253, v[212:215]
	v_mfma_f32_16x16x4_f32 v[216:219], v193, v253, v[216:219]
	v_mfma_f32_16x16x4_f32 v[220:223], v197, v253, v[220:223]
	v_mfma_f32_16x16x4_f32 v[248:251], v134, v252, v[72:75]
	v_mfma_f32_16x16x4_f32 v[248:251], v135, v253, v[248:251]
.Lmy_f_pfjoin:
	s_waitcnt lgkmcnt(3)
	v_pk_mul_f32 v[208:209], v[208:209], v[140:141]
	v_pk_mul_f32 v[210:211], v[210:211], v[142:143]
	s_waitcnt lgkmcnt(2)
	v_pk_mul_f32 v[212:213], v[212:213], v[144:145]
	v_pk_mul_f32 v[214:215], v[214:215], v[146:147]
	s_waitcnt lgkmcnt(1)
	v_pk_mul_f32 v[216:217], v[216:217], v[148:149]
	v_pk_mul_f32 v[218:219], v[218:219], v[150:151]
	s_waitcnt lgkmcnt(0)
	v_pk_mul_f32 v[220:221], v[220:221], v[152:153]
	v_pk_mul_f32 v[222:223], v[222:223], v[154:155]
	s_mov_b64 exec, s[98:99]
	s_nop 0
	ds_write_b32 v231, v248 offset:6144
	ds_write_b32 v231, v249 offset:6400
	ds_write_b32 v231, v250 offset:6656
	ds_write_b32 v231, v251 offset:6912
	s_mov_b64 exec, -1
	s_branch .LBB0_655

.Lmy_ck_drE_h:
	s_waitcnt lgkmcnt(0)
	s_bfe_u32 s96, s62, 0x20006
	s_and_b32 s97, s96, 1
	s_mul_i32 s97, s97, 0x2700
	s_mov_b32 s101, 0x1c000
	s_mov_b32 s100, 0x6100
	s_bitcmp0_b32 s65, 0
	s_cselect_b32 s101, 0xe000, s101
	s_cselect_b32 s100, 0x4e00, s100
	s_cmp_gt_u32 s96, 1
	s_cselect_b32 s100, s100, 0
	s_add_i32 s97, s97, s101
	s_add_i32 s97, s97, s100
	s_mov_b32 s96, s97
	v_and_b32_e32 v72, 3, v233
	v_lshrrev_b32_e32 v73, 2, v233
	v_lshlrev_b32_e32 v72, 2, v72
	v_lshl_add_u32 v72, v73, 8, v72
	v_lshl_add_u32 v72, v234, 6, v72
	s_add_i32 s97, s96, 0x1000
	v_add_u32_e32 v78, s97, v72
	v_xor_b32_e32 v79, v224, v234
	v_lshl_add_u32 v79, v79, 4, s96
	ds_read_b128 v[96:99], v79
	ds_read_b128 v[100:103], v79 offset:1024
	ds_read_b128 v[104:107], v79 offset:2048
	ds_read_b128 v[108:111], v79 offset:3072
	ds_read_b32 v80, v78
	ds_read_b32 v81, v78 offset:16
	ds_read_b32 v82, v78 offset:32
	ds_read_b32 v83, v78 offset:48
	ds_read_b32 v84, v78 offset:1024
	ds_read_b32 v85, v78 offset:1040
	ds_read_b32 v86, v78 offset:1056
	ds_read_b32 v87, v78 offset:1072
	ds_read_b32 v88, v78 offset:2048
	ds_read_b32 v89, v78 offset:2064
	ds_read_b32 v90, v78 offset:2080
	ds_read_b32 v91, v78 offset:2096
	ds_read_b32 v92, v78 offset:3072
	ds_read_b32 v93, v78 offset:3088
	ds_read_b32 v94, v78 offset:3104
	ds_read_b32 v95, v78 offset:3120
	v_lshl_add_u32 v74, v224, 2, s96
	ds_write_b32 v74, v235 offset:9728
	v_add_u32_e32 v75, -1, v233
	v_mov_b32_e32 v76, -1
	v_cndmask_b32_e64 v75, v76, v75, s[98:99]
	v_cmp_lt_u32_e64 s[100:101], 7, v233
	v_add_u32_e32 v76, -8, v233
	v_and_b32_e32 v77, 1, v234
	v_cndmask_b32_e64 v75, v75, v76, s[100:101]
	v_lshlrev_b32_e32 v77, 2, v77
	v_sub_u32_e32 v76, v75, v77
	v_lshlrev_b32_e32 v77, 2, v234
	v_sub_u32_e32 v77, v233, v77
	v_add_u32_e32 v77, -1, v77
	s_waitcnt lgkmcnt(15)
	v_mfma_f32_16x16x4_f32 v[244:247], v80, v96, 0
	v_mfma_f32_16x16x4_f32 v[240:243], v81, v97, 0
	s_waitcnt lgkmcnt(14)
	v_mfma_f32_16x16x4_f32 v[244:247], v82, v98, v[244:247]
	s_waitcnt lgkmcnt(13)
	v_mfma_f32_16x16x4_f32 v[240:243], v83, v99, v[240:243]
	s_waitcnt lgkmcnt(12)
	v_mfma_f32_16x16x4_f32 v[244:247], v84, v100, v[244:247]
	s_waitcnt lgkmcnt(11)
	v_mfma_f32_16x16x4_f32 v[240:243], v85, v101, v[240:243]
	s_waitcnt lgkmcnt(10)
	v_mfma_f32_16x16x4_f32 v[244:247], v86, v102, v[244:247]
	s_waitcnt lgkmcnt(9)
	v_mfma_f32_16x16x4_f32 v[240:243], v87, v103, v[240:243]
	s_waitcnt lgkmcnt(8)
	v_mfma_f32_16x16x4_f32 v[244:247], v88, v104, v[244:247]
	s_waitcnt lgkmcnt(7)
	v_mfma_f32_16x16x4_f32 v[240:243], v89, v105, v[240:243]
	s_waitcnt lgkmcnt(6)
	v_mfma_f32_16x16x4_f32 v[244:247], v90, v106, v[244:247]
	s_waitcnt lgkmcnt(5)
	v_mfma_f32_16x16x4_f32 v[240:243], v91, v107, v[240:243]
	s_waitcnt lgkmcnt(4)
	v_mfma_f32_16x16x4_f32 v[244:247], v92, v108, v[244:247]
	s_waitcnt lgkmcnt(3)
	v_mfma_f32_16x16x4_f32 v[240:243], v93, v109, v[240:243]
	s_waitcnt lgkmcnt(2)
	v_mfma_f32_16x16x4_f32 v[244:247], v94, v110, v[244:247]
	s_waitcnt lgkmcnt(1)
	v_mfma_f32_16x16x4_f32 v[240:243], v95, v111, v[240:243]
	s_nop 9
	v_add_f32_e32 v244, v244, v240
	v_add_f32_e32 v245, v245, v241
	v_add_f32_e32 v246, v246, v242
	v_add_f32_e32 v247, v247, v243
	v_cmp_le_i32_e64 s[96:97], 0, v76
	v_cmp_le_i32_e64 s[100:101], 1, v76
	s_nop 0
	v_cndmask_b32_e64 v128, 0, v244, s[96:97]
	v_cndmask_b32_e64 v129, 0, v245, s[100:101]
	v_cmp_le_i32_e64 s[96:97], 2, v76
	v_cmp_le_i32_e64 s[100:101], 3, v76
	s_nop 0
	v_cndmask_b32_e64 v130, 0, v246, s[96:97]
	v_cndmask_b32_e64 v131, 0, v247, s[100:101]
	s_bfe_u32 s96, s62, 0x20006
	s_and_b32 s97, s96, 1
	s_mul_i32 s97, s97, 0x2700
	s_mov_b32 s101, 0x1c000
	s_mov_b32 s100, 0x6100
	s_bitcmp0_b32 s65, 0
	s_cselect_b32 s101, 0xe000, s101
	s_cselect_b32 s100, 0x4e00, s100
	s_cmp_gt_u32 s96, 1
	s_cselect_b32 s100, s100, 0
	s_add_i32 s97, s97, s101
	s_add_i32 s97, s97, s100
	v_xor_b32_e32 v74, v224, v234
	v_lshl_add_u32 v74, v74, 4, s97
	ds_write_b128 v74, v[128:131] offset:8448
	v_lshlrev_b32_e32 v75, 7, v234
	v_lshl_add_u32 v75, v233, 2, v75
	v_add_u32_e32 v75, s97, v75
	v_cmp_le_i32_e64 s[96:97], 0, v77
	v_cmp_le_i32_e64 s[100:101], 1, v77
	s_nop 0
	v_cndmask_b32_e64 v132, 0, v244, s[96:97]
	v_cndmask_b32_e64 v133, 0, v245, s[100:101]
	v_cmp_le_i32_e64 s[96:97], 2, v77
	v_cmp_le_i32_e64 s[100:101], 3, v77
	s_nop 0
	v_cndmask_b32_e64 v134, 0, v246, s[96:97]
	v_cndmask_b32_e64 v135, 0, v247, s[100:101]
	s_mov_b64 exec, 0x00ff00ff
	ds_write_b32 v75, v132 offset:9472
	ds_write_b32 v75, v133 offset:9504
	ds_write_b32 v75, v134 offset:9536
	ds_write_b32 v75, v135 offset:9568
	s_mov_b64 exec, -1
	s_cmpk_eq_u32 s62, 0x100
	s_cbranch_scc0 .Lmy_f_noflag
	v_mov_b32_e32 v72, 0x22040
	v_mov_b32_e32 v73, s22
	ds_write_b32 v72, v73
.Lmy_f_noflag:
	s_setprio 0
	s_branch .LBB0_655
	s_nop 0
	s_nop 0
	s_nop 0
	s_nop 0
	s_nop 0
	s_nop 0
	s_nop 0
	s_nop 0
	s_nop 0
	s_nop 0
	s_nop 0
	s_nop 0
	s_nop 0
	s_nop 0
	s_nop 0
	s_nop 0
	s_nop 0
	s_nop 0
	s_nop 0
	s_nop 0
	s_nop 0
	s_nop 0
	s_nop 0
	s_nop 0
	s_nop 0
	s_nop 0
	s_nop 0
	s_nop 0
	s_nop 0
	s_nop 0
	s_nop 0
	s_nop 0
	s_nop 0
	s_nop 0
	s_nop 0
	s_nop 0
	s_nop 0
	s_nop 0
	s_nop 0
	s_nop 0
	s_nop 0
	s_nop 0
	s_nop 0
	s_nop 0
	s_nop 0
	s_nop 0
	s_nop 0
	s_nop 0
	s_nop 0
	s_nop 0
	s_nop 0
	s_nop 0
	s_nop 0
	s_nop 0
	s_nop 0
	s_nop 0
